# v36 + NSA tile loop: four filler nops dropped where neighbouring instructions already provide the wait states
# baseline (speedup 1.0000x reference)
; #define LAS __attribute__((address_space(3)))
; DI f32x16 mma32(bf16x8 a, bf16x8 b, f32x16 c) { return __builtin_amdgcn_mfma_f32_32x32x16_bf16(a, b, c, 0, 0, 0); }
; DI int crow(int i, int hf) { return (i & 3) + 8 * (i >> 2) + 4 * hf; }
; DI void nsa_item(KA a, LAS unsigned char* lds, const int it) {
;     ...
;         const int desc = LIST[i]; const int ty = desc >> 8, j = desc & 255;
;         const LAS bf16* Kc = (i & 1) ? Kt1 : Kt; const LAS bf16* Vc = (i & 1) ? VT1 : VT;
;         if (ty != curtype) { const float lt = l_run + __shfl_xor(l_run, 32); const float sc = g1 / lt; of[0] += ot[0] * sc; of[1] += ot[1] * sc; ot[0] = ZERO16; ot[1] = ZERO16; m_ref = 0.f; l_run = 0.f; curtype = ty; }
;         const bool rowoff = (ty == 0) && (((mysel >> j) & 1u) == 0u);
;         const int mode = (j == qb) ? 1 : ((ty == 1 && j == qb - 8) ? 2 : 0);
;         const float init = rowoff ? -INFINITY : -m_ref;
;         f32x16 st[2];
; #pragma unroll
;         for (int i2 = 0; i2 < 16; ++i2) { st[0][i2] = init; st[1][i2] = init; }
; #pragma unroll
;         for (int kt = 0; kt < 2; ++kt)
; #pragma unroll
;             for (int s = 0; s < 4; ++s) { const bf16x8 af = *(const LAS bf16x8*)(Kc + (32 * kt + r) * PA + 16 * s + 8 * hf); st[kt] = mma32(af, bq[s], st[kt]); }
;         if (mode != 0) {
; #pragma unroll
;             for (int kt = 0; kt < 2; ++kt)
; #pragma unroll
;                 for (int i2 = 0; i2 < 16; ++i2) { const int kl = 32 * kt + crow(i2, hf); const bool bad = rowoff || (mode == 1 && kl > tql) || (mode == 2 && kl <= tql); st[kt][i2] = bad ? -INFINITY : st[kt][i2]; }
;         }
.LBB0_798:
	s_and_b32 s83, s78, 0xff
	s_cmpk_lt_u32 s78, 0x100
	s_cselect_b64 s[80:81], -1, 0
	s_lshl_b32 s78, 1, s78
	v_and_b32_e32 v32, s78, v141
	v_cmp_eq_u32_e32 vcc, 0, v32
	s_and_b64 s[78:79], s[80:81], vcc
	v_cndmask_b32_e64 v32, -v137, v240, s[78:79]
	v_mov_b32_e32 v33, v32
	v_mov_b64_e32 v[34:35], v[32:33]
	v_mov_b64_e32 v[36:37], v[32:33]
	v_mov_b64_e32 v[38:39], v[32:33]
	v_mov_b64_e32 v[40:41], v[32:33]
	v_mov_b64_e32 v[42:43], v[32:33]
	v_mov_b64_e32 v[44:45], v[32:33]
	v_mov_b64_e32 v[46:47], v[32:33]
	s_cmp_eq_u32 s83, s90
	s_cselect_b64 s[80:81], -1, 0
	v_mfma_f32_32x32x16_bf16 v[48:63], v[170:173], v[68:71], v[32:47]
	s_cmp_eq_u32 s83, s85
	s_cselect_b64 vcc, -1, 0
	s_cmp_eq_u32 s82, 1
	s_cselect_b64 s[82:83], -1, 0
	s_and_b64 s[82:83], s[82:83], vcc
	s_or_b64 vcc, s[80:81], s[82:83]
	s_andn2_b64 vcc, exec, vcc
	v_mfma_f32_32x32x16_bf16 v[32:47], v[178:181], v[72:75], v[32:47]
	v_mfma_f32_32x32x16_bf16 v[32:47], v[182:185], v[64:67], v[32:47]
	v_mfma_f32_32x32x16_bf16 v[32:47], v[186:189], v[68:71], v[32:47]
	v_mfma_f32_32x32x16_bf16 v[32:47], v[206:209], v[76:79], v[32:47]
	v_mfma_f32_32x32x16_bf16 v[48:63], v[174:177], v[76:79], v[48:63]
	s_waitcnt lgkmcnt(1)
	v_mfma_f32_32x32x16_bf16 v[48:63], v[144:147], v[72:75], v[48:63]
	s_waitcnt lgkmcnt(0)
	v_mfma_f32_32x32x16_bf16 v[48:63], v[148:151], v[64:67], v[48:63]
	ds_read_b128 v[148:151], v230 offset:8800
	s_cbranch_vccnz .LBB0_800
	s_and_b64 vcc, exec, s[80:81]
	s_nop 0
	s_cbranch_vccz .Lnsa_m2
	v_cmp_gt_i32_e64 s[74:75], 32, v242
	v_cmp_gt_i32_e64 s[76:77], 33, v242
	v_cmp_gt_i32_e64 s[78:79], 34, v242
	v_cndmask_b32_e64 v32, v32, v240, s[74:75]
	v_cmp_gt_i32_e64 s[74:75], 35, v242
	v_cndmask_b32_e64 v33, v33, v240, s[76:77]
	v_cmp_gt_i32_e64 s[76:77], 40, v242
	v_cndmask_b32_e64 v34, v34, v240, s[78:79]
	v_cmp_gt_i32_e64 s[78:79], 41, v242
	v_cndmask_b32_e64 v35, v35, v240, s[74:75]
	v_cmp_gt_i32_e64 s[74:75], 42, v242
	v_cndmask_b32_e64 v36, v36, v240, s[76:77]
	v_cmp_gt_i32_e64 s[76:77], 43, v242
	v_cndmask_b32_e64 v37, v37, v240, s[78:79]
	v_cmp_gt_i32_e64 s[78:79], 48, v242
	v_cndmask_b32_e64 v38, v38, v240, s[74:75]
	v_cmp_gt_i32_e64 s[74:75], 49, v242
	v_cndmask_b32_e64 v39, v39, v240, s[76:77]
	v_cmp_gt_i32_e64 s[76:77], 50, v242
	v_cndmask_b32_e64 v40, v40, v240, s[78:79]
	v_cmp_gt_i32_e64 s[78:79], 51, v242
	v_cndmask_b32_e64 v41, v41, v240, s[74:75]
	v_cmp_gt_i32_e64 s[74:75], 56, v242
	v_cndmask_b32_e64 v42, v42, v240, s[76:77]
	v_cmp_gt_i32_e64 s[76:77], 57, v242
	v_cndmask_b32_e64 v43, v43, v240, s[78:79]
	v_cmp_gt_i32_e64 s[78:79], 58, v242
	v_cndmask_b32_e64 v44, v44, v240, s[74:75]
	v_cmp_gt_i32_e64 s[74:75], 59, v242
	v_cndmask_b32_e64 v45, v45, v240, s[76:77]
	v_cmp_gt_i32_e64 s[76:77], 0, v242
	v_cndmask_b32_e64 v46, v46, v240, s[78:79]
	v_cmp_gt_i32_e64 s[78:79], 1, v242
	v_cndmask_b32_e64 v47, v47, v240, s[74:75]
	v_cmp_gt_i32_e64 s[74:75], 2, v242
	v_cndmask_b32_e64 v48, v48, v240, s[76:77]
	v_cmp_gt_i32_e64 s[76:77], 3, v242
	v_cndmask_b32_e64 v49, v49, v240, s[78:79]
	v_cmp_gt_i32_e64 s[78:79], 8, v242
	v_cndmask_b32_e64 v50, v50, v240, s[74:75]
	v_cmp_gt_i32_e64 s[74:75], 9, v242
	v_cndmask_b32_e64 v51, v51, v240, s[76:77]
	v_cmp_gt_i32_e64 s[76:77], 10, v242
	v_cndmask_b32_e64 v52, v52, v240, s[78:79]
	v_cmp_gt_i32_e64 s[78:79], 11, v242
	v_cndmask_b32_e64 v53, v53, v240, s[74:75]
	v_cmp_gt_i32_e64 s[74:75], 16, v242
	v_cndmask_b32_e64 v54, v54, v240, s[76:77]
	v_cmp_gt_i32_e64 s[76:77], 17, v242
	v_cndmask_b32_e64 v55, v55, v240, s[78:79]
	v_cmp_gt_i32_e64 s[78:79], 18, v242
	v_cndmask_b32_e64 v56, v56, v240, s[74:75]
	v_cmp_gt_i32_e64 s[74:75], 19, v242
	v_cndmask_b32_e64 v57, v57, v240, s[76:77]
	v_cmp_gt_i32_e64 s[76:77], 24, v242
	v_cndmask_b32_e64 v58, v58, v240, s[78:79]
	v_cmp_gt_i32_e64 s[78:79], 25, v242
	v_cndmask_b32_e64 v59, v59, v240, s[74:75]
	v_cmp_gt_i32_e64 s[74:75], 26, v242
	v_cndmask_b32_e64 v60, v60, v240, s[76:77]
	v_cmp_gt_i32_e64 s[76:77], 27, v242
	s_nop 0
	v_cndmask_b32_e64 v61, v61, v240, s[78:79]
	v_cndmask_b32_e64 v62, v62, v240, s[74:75]
	v_cndmask_b32_e64 v63, v63, v240, s[76:77]
	s_branch .LBB0_800

; DI f32x16 mma32(bf16x8 a, bf16x8 b, f32x16 c) { return __builtin_amdgcn_mfma_f32_32x32x16_bf16(a, b, c, 0, 0, 0); }
; DI bf16x8 packp(const f32x16& x, const int h8) { v4u p; p.x = pk2(x[h8 + 0], x[h8 + 1]); p.y = pk2(x[h8 + 2], x[h8 + 3]); p.z = pk2(x[h8 + 4], x[h8 + 5]); p.w = pk2(x[h8 + 6], x[h8 + 7]); return __builtin_bit_cast(bf16x8, p); }
; #define NSA_STORE(Kb, Vb) do { *(LAS v4u*)((Kb) + skey * PA + 8 * sch) = kreg; LAS unsigned* d0_ = (LAS unsigned*)((Vb) + (4 * sdg) * PV + vpos(2 * skp)); \
;         d0_[0] = (vr0.x & 0xffffu) | (vr1.x << 16); d0_[PV / 2] = (vr0.x >> 16) | (vr1.x & 0xffff0000u); d0_[PV] = (vr0.y & 0xffffu) | (vr1.y << 16); d0_[3 * PV / 2] = (vr0.y >> 16) | (vr1.y & 0xffff0000u); } while (0)
; DI void nsa_item(KA a, LAS unsigned char* lds, const int it) {
;     ...
;         float mx = -INFINITY;
; #pragma unroll
;         for (int kt = 0; kt < 2; ++kt)
; #pragma unroll
;             for (int i2 = 0; i2 < 16; ++i2) mx = fmaxf(mx, st[kt][i2]);
;         mx = fmaxf(mx, __shfl_xor(mx, 32));
;         const bool drift = (fabsf(mx) > 24.f) && (mx > -INFINITY);
;         if (__any(drift)) {
;             const float d = drift ? mx : 0.f, scl = __builtin_amdgcn_exp2f(-d); m_ref += d; l_run *= scl; ot[0] = ot[0] * scl; ot[1] = ot[1] * scl;
; #pragma unroll
;             for (int kt = 0; kt < 2; ++kt)
; #pragma unroll
;                 for (int i2 = 0; i2 < 16; ++i2) st[kt][i2] -= d;
;         }
;         f32x2 ls2 = {0.f, 0.f};
; #pragma unroll
;         for (int kt = 0; kt < 2; ++kt)
; #pragma unroll
;             for (int i2 = 0; i2 < 16; i2 += 2) { const float p0 = __builtin_amdgcn_exp2f(st[kt][i2]), p1 = __builtin_amdgcn_exp2f(st[kt][i2 + 1]); st[kt][i2] = p0; st[kt][i2 + 1] = p1; ls2 += (f32x2){p0, p1}; }
;         l_run += ls2[0] + ls2[1];
; #pragma unroll
;         for (int sp = 0; sp < 4; ++sp) { const bf16x8 pf = packp(st[sp >> 1], 8 * (sp & 1));
; #pragma unroll
;             for (int dh = 0; dh < 2; ++dh) ot[dh] = mma32(vfrag(Vc, 32 * dh + r, sp, hf), pf, ot[dh]); }
;         if (i + 1 < n) { if (i & 1) NSA_STORE(Kt, VT); else NSA_STORE(Kt1, VT1); if (i + 2 < n) NSA_LOAD(LIST[i + 2]); }
;         __syncthreads();
.Lnsa_rsskip:
	s_mov_b32 s80, 0xff800000
	v_max3_f32 v89, v48, s80, v49
	v_max3_f32 v89, v89, v50, v51
	v_max3_f32 v89, v89, v52, v53
	v_max3_f32 v89, v89, v54, v55
	v_max3_f32 v89, v89, v56, v57
	v_max3_f32 v89, v89, v58, v59
	v_max3_f32 v89, v89, v60, v61
	v_max3_f32 v89, v89, v62, v63
	v_max3_f32 v89, v89, v32, v33
	v_max3_f32 v89, v89, v34, v35
	v_max3_f32 v89, v89, v36, v37
	v_max3_f32 v89, v89, v38, v39
	v_max3_f32 v89, v89, v40, v41
	v_max3_f32 v89, v89, v42, v43
	v_max3_f32 v89, v89, v44, v45
	v_max3_f32 v89, v89, v46, v47
	v_mov_b32_e32 v139, v89
	s_mov_b32 s78, 0x41c00000
	s_movk_i32 s81, 0x1ff
	v_permlane32_swap_b32_e32 v139, v89
	v_max_f32_e32 v89, v89, v139
	v_cmp_gt_f32_e64 s[78:79], |v89|, s78
	v_cmp_lg_f32_e32 vcc, s80, v89
	s_and_b64 vcc, vcc, s[78:79]
	s_cbranch_vccz .LBB0_802
	v_cndmask_b32_e32 v140, 0, v89, vcc
	v_exp_f32_e64 v144, -v140
	v_add_f32_e32 v137, v137, v140
	v_pk_add_f32 v[48:49], v[48:49], v[140:141] op_sel_hi:[1,0] neg_lo:[0,1] neg_hi:[0,1]
	v_pk_add_f32 v[50:51], v[50:51], v[140:141] op_sel_hi:[1,0] neg_lo:[0,1] neg_hi:[0,1]
	v_pk_mul_f32 v[30:31], v[30:31], v[144:145] op_sel_hi:[1,0]
	v_pk_mul_f32 v[28:29], v[28:29], v[144:145] op_sel_hi:[1,0]
	v_pk_mul_f32 v[26:27], v[26:27], v[144:145] op_sel_hi:[1,0]
	v_pk_mul_f32 v[24:25], v[24:25], v[144:145] op_sel_hi:[1,0]
	v_pk_mul_f32 v[22:23], v[22:23], v[144:145] op_sel_hi:[1,0]
	v_pk_mul_f32 v[20:21], v[20:21], v[144:145] op_sel_hi:[1,0]
	v_pk_mul_f32 v[18:19], v[18:19], v[144:145] op_sel_hi:[1,0]
	v_pk_mul_f32 v[16:17], v[16:17], v[144:145] op_sel_hi:[1,0]
	v_pk_mul_f32 v[14:15], v[14:15], v[144:145] op_sel_hi:[1,0]
	v_pk_mul_f32 v[12:13], v[12:13], v[144:145] op_sel_hi:[1,0]
	v_pk_mul_f32 v[10:11], v[10:11], v[144:145] op_sel_hi:[1,0]
	v_pk_mul_f32 v[8:9], v[8:9], v[144:145] op_sel_hi:[1,0]
	v_pk_mul_f32 v[6:7], v[6:7], v[144:145] op_sel_hi:[1,0]
	v_pk_mul_f32 v[4:5], v[4:5], v[144:145] op_sel_hi:[1,0]
	v_pk_mul_f32 v[2:3], v[2:3], v[144:145] op_sel_hi:[1,0]
	v_pk_mul_f32 v[0:1], v[0:1], v[144:145] op_sel_hi:[1,0]
	v_pk_add_f32 v[52:53], v[52:53], v[140:141] op_sel_hi:[1,0] neg_lo:[0,1] neg_hi:[0,1]
	v_pk_add_f32 v[54:55], v[54:55], v[140:141] op_sel_hi:[1,0] neg_lo:[0,1] neg_hi:[0,1]
	v_pk_add_f32 v[56:57], v[56:57], v[140:141] op_sel_hi:[1,0] neg_lo:[0,1] neg_hi:[0,1]
	v_pk_add_f32 v[58:59], v[58:59], v[140:141] op_sel_hi:[1,0] neg_lo:[0,1] neg_hi:[0,1]
	v_pk_add_f32 v[60:61], v[60:61], v[140:141] op_sel_hi:[1,0] neg_lo:[0,1] neg_hi:[0,1]
	v_pk_add_f32 v[62:63], v[62:63], v[140:141] op_sel_hi:[1,0] neg_lo:[0,1] neg_hi:[0,1]
	v_pk_add_f32 v[32:33], v[32:33], v[140:141] op_sel_hi:[1,0] neg_lo:[0,1] neg_hi:[0,1]
	v_pk_add_f32 v[34:35], v[34:35], v[140:141] op_sel_hi:[1,0] neg_lo:[0,1] neg_hi:[0,1]
	v_pk_add_f32 v[36:37], v[36:37], v[140:141] op_sel_hi:[1,0] neg_lo:[0,1] neg_hi:[0,1]
	v_pk_add_f32 v[38:39], v[38:39], v[140:141] op_sel_hi:[1,0] neg_lo:[0,1] neg_hi:[0,1]
	v_pk_add_f32 v[40:41], v[40:41], v[140:141] op_sel_hi:[1,0] neg_lo:[0,1] neg_hi:[0,1]
	v_pk_add_f32 v[42:43], v[42:43], v[140:141] op_sel_hi:[1,0] neg_lo:[0,1] neg_hi:[0,1]
	v_pk_add_f32 v[44:45], v[44:45], v[140:141] op_sel_hi:[1,0] neg_lo:[0,1] neg_hi:[0,1]
	v_pk_add_f32 v[46:47], v[46:47], v[140:141] op_sel_hi:[1,0] neg_lo:[0,1] neg_hi:[0,1]
	v_mul_f32_e32 v135, v135, v144
.LBB0_802:
	s_waitcnt lgkmcnt(0)
	s_barrier
	s_bitcmp1_b32 s87, 0
	s_cselect_b32 s74, 0, 0x9000
	s_movk_i32 s75, 0x4800
	s_cselect_b32 s75, s75, 0xb400
	v_add3_u32 v231, s74, v90, v130
	v_add3_u32 v230, s75, v90, v131
	ds_read_b128 v[170:173], v231 offset:64
	ds_read_b128 v[178:181], v231 offset:4608
	ds_read_b128 v[182:185], v231 offset:4640
	ds_read_b128 v[186:189], v231 offset:4672
	ds_read_b128 v[206:209], v231 offset:4704
	ds_read_b128 v[174:177], v231 offset:96
	v_exp_f32_e32 v48, v48
	v_exp_f32_e32 v49, v49
	v_exp_f32_e32 v50, v50
	v_exp_f32_e32 v51, v51
	v_exp_f32_e32 v52, v52
	v_exp_f32_e32 v53, v53
	v_exp_f32_e32 v54, v54
	v_exp_f32_e32 v55, v55
	v_cvt_pk_bf16_f32 v144, v48, v49
	v_cvt_pk_bf16_f32 v145, v50, v51
	v_cvt_pk_bf16_f32 v146, v52, v53
	v_cvt_pk_bf16_f32 v147, v54, v55
	v_exp_f32_e32 v56, v56
	v_exp_f32_e32 v57, v57
	v_mfma_f32_32x32x16_bf16 v[16:31], v[210:213], v[144:147], v[16:31]
	v_exp_f32_e32 v58, v58
	v_exp_f32_e32 v59, v59
	v_exp_f32_e32 v60, v60
	v_exp_f32_e32 v61, v61
	v_exp_f32_e32 v62, v62
	v_exp_f32_e32 v63, v63
	v_mfma_f32_32x32x16_bf16 v[0:15], v[218:221], v[144:147], v[0:15]
	v_cvt_pk_bf16_f32 v144, v56, v57
	v_cvt_pk_bf16_f32 v145, v58, v59
	v_cvt_pk_bf16_f32 v146, v60, v61
	v_cvt_pk_bf16_f32 v147, v62, v63
	v_exp_f32_e32 v32, v32
	v_exp_f32_e32 v33, v33
	v_mfma_f32_32x32x16_bf16 v[0:15], v[222:225], v[144:147], v[0:15]
	v_exp_f32_e32 v34, v34
	v_exp_f32_e32 v35, v35
	v_exp_f32_e32 v36, v36
	v_exp_f32_e32 v37, v37
	v_exp_f32_e32 v38, v38
	v_exp_f32_e32 v39, v39
	v_mfma_f32_32x32x16_bf16 v[16:31], v[214:217], v[144:147], v[16:31]
	v_cvt_pk_bf16_f32 v144, v32, v33
	v_cvt_pk_bf16_f32 v145, v34, v35
	v_cvt_pk_bf16_f32 v146, v36, v37
	v_cvt_pk_bf16_f32 v147, v38, v39
	v_exp_f32_e32 v40, v40
	v_exp_f32_e32 v41, v41
	v_exp_f32_e32 v42, v42
	v_mfma_f32_32x32x16_bf16 v[16:31], v[226:229], v[144:147], v[16:31]
	v_exp_f32_e32 v43, v43
	v_exp_f32_e32 v44, v44
	v_exp_f32_e32 v45, v45
	v_exp_f32_e32 v46, v46
	v_exp_f32_e32 v47, v47
	s_add_i32 s76, s87, 1
	v_mfma_f32_32x32x16_bf16 v[0:15], v[152:155], v[144:147], v[0:15]
	v_cvt_pk_bf16_f32 v144, v40, v41
	v_cvt_pk_bf16_f32 v145, v42, v43
	v_cvt_pk_bf16_f32 v146, v44, v45
	v_cvt_pk_bf16_f32 v147, v46, v47
	s_nop 1
	v_mfma_f32_32x32x16_bf16 v[16:31], v[246:249], v[144:147], v[16:31]
	v_mfma_f32_32x32x16_bf16 v[0:15], v[148:151], v[144:147], v[0:15]
